# out/down projection tile epilogues: row-sum butterfly (xor 16, 32) via v_permlane16/32_swap instead of ds_bpermute
# baseline (speedup 1.0000x reference)
.LBB0_713:
	v_xor_b32_e32 v140, 16, v230
	v_xor_b32_e32 v141, 32, v230
	v_lshlrev_b32_e32 v140, 2, v140
	v_lshlrev_b32_e32 v141, 2, v141
	s_mov_b64 s[100:101], s[46:47]
	s_waitcnt vmcnt(14)
	v_lshlrev_b32_e32 v142, 16, v148
	v_and_b32_e32 v143, 0xffff0000, v148
	v_pk_add_f32 v[124:125], v[124:125], v[142:143]
	v_pk_mul_f32 v[222:223], v[124:125], v[124:125]
	v_cvt_pk_bf16_f32 v148, v124, v125
	v_lshlrev_b32_e32 v142, 16, v149
	v_and_b32_e32 v143, 0xffff0000, v149
	v_pk_add_f32 v[126:127], v[126:127], v[142:143]
	v_pk_fma_f32 v[222:223], v[126:127], v[126:127], v[222:223]
	v_cvt_pk_bf16_f32 v149, v126, v127
	v_lshlrev_b32_e32 v142, 16, v150
	v_and_b32_e32 v143, 0xffff0000, v150
	v_pk_add_f32 v[120:121], v[120:121], v[142:143]
	v_pk_fma_f32 v[222:223], v[120:121], v[120:121], v[222:223]
	v_cvt_pk_bf16_f32 v150, v120, v121
	v_lshlrev_b32_e32 v142, 16, v151
	v_and_b32_e32 v143, 0xffff0000, v151
	v_pk_add_f32 v[122:123], v[122:123], v[142:143]
	v_pk_fma_f32 v[222:223], v[122:123], v[122:123], v[222:223]
	v_cvt_pk_bf16_f32 v151, v122, v123
	global_store_dwordx4 v138, v[148:151], s[100:101]
	v_lshlrev_b32_e32 v142, 16, v152
	v_and_b32_e32 v143, 0xffff0000, v152
	v_pk_add_f32 v[116:117], v[116:117], v[142:143]
	v_pk_fma_f32 v[222:223], v[116:117], v[116:117], v[222:223]
	v_cvt_pk_bf16_f32 v152, v116, v117
	v_lshlrev_b32_e32 v142, 16, v153
	v_and_b32_e32 v143, 0xffff0000, v153
	v_pk_add_f32 v[118:119], v[118:119], v[142:143]
	v_pk_fma_f32 v[222:223], v[118:119], v[118:119], v[222:223]
	v_cvt_pk_bf16_f32 v153, v118, v119
	v_lshlrev_b32_e32 v142, 16, v154
	v_and_b32_e32 v143, 0xffff0000, v154
	v_pk_add_f32 v[112:113], v[112:113], v[142:143]
	v_pk_fma_f32 v[222:223], v[112:113], v[112:113], v[222:223]
	v_cvt_pk_bf16_f32 v154, v112, v113
	v_lshlrev_b32_e32 v142, 16, v155
	v_and_b32_e32 v143, 0xffff0000, v155
	v_pk_add_f32 v[114:115], v[114:115], v[142:143]
	v_pk_fma_f32 v[222:223], v[114:115], v[114:115], v[222:223]
	v_cvt_pk_bf16_f32 v155, v114, v115
	global_store_dwordx4 v138, v[152:155], s[100:101] offset:256
	v_add_f32_e32 v124, v222, v223
	s_add_u32 s100, s100, 0x8000
	s_addc_u32 s101, s101, 0
	s_waitcnt vmcnt(14)
	v_lshlrev_b32_e32 v142, 16, v156
	v_and_b32_e32 v143, 0xffff0000, v156
	v_pk_add_f32 v[108:109], v[108:109], v[142:143]
	v_pk_mul_f32 v[222:223], v[108:109], v[108:109]
	v_cvt_pk_bf16_f32 v156, v108, v109
	v_lshlrev_b32_e32 v142, 16, v157
	v_and_b32_e32 v143, 0xffff0000, v157
	v_pk_add_f32 v[110:111], v[110:111], v[142:143]
	v_pk_fma_f32 v[222:223], v[110:111], v[110:111], v[222:223]
	v_cvt_pk_bf16_f32 v157, v110, v111
	v_lshlrev_b32_e32 v142, 16, v158
	v_and_b32_e32 v143, 0xffff0000, v158
	v_pk_add_f32 v[104:105], v[104:105], v[142:143]
	v_pk_fma_f32 v[222:223], v[104:105], v[104:105], v[222:223]
	v_cvt_pk_bf16_f32 v158, v104, v105
	v_lshlrev_b32_e32 v142, 16, v159
	v_and_b32_e32 v143, 0xffff0000, v159
	v_pk_add_f32 v[106:107], v[106:107], v[142:143]
	v_pk_fma_f32 v[222:223], v[106:107], v[106:107], v[222:223]
	v_cvt_pk_bf16_f32 v159, v106, v107
	global_store_dwordx4 v138, v[156:159], s[100:101]
	v_lshlrev_b32_e32 v142, 16, v160
	v_and_b32_e32 v143, 0xffff0000, v160
	v_pk_add_f32 v[100:101], v[100:101], v[142:143]
	v_pk_fma_f32 v[222:223], v[100:101], v[100:101], v[222:223]
	v_cvt_pk_bf16_f32 v160, v100, v101
	v_lshlrev_b32_e32 v142, 16, v161
	v_and_b32_e32 v143, 0xffff0000, v161
	v_pk_add_f32 v[102:103], v[102:103], v[142:143]
	v_pk_fma_f32 v[222:223], v[102:103], v[102:103], v[222:223]
	v_cvt_pk_bf16_f32 v161, v102, v103
	v_lshlrev_b32_e32 v142, 16, v162
	v_and_b32_e32 v143, 0xffff0000, v162
	v_pk_add_f32 v[96:97], v[96:97], v[142:143]
	v_pk_fma_f32 v[222:223], v[96:97], v[96:97], v[222:223]
	v_cvt_pk_bf16_f32 v162, v96, v97
	v_lshlrev_b32_e32 v142, 16, v163
	v_and_b32_e32 v143, 0xffff0000, v163
	v_pk_add_f32 v[98:99], v[98:99], v[142:143]
	v_pk_fma_f32 v[222:223], v[98:99], v[98:99], v[222:223]
	v_cvt_pk_bf16_f32 v163, v98, v99
	global_store_dwordx4 v138, v[160:163], s[100:101] offset:256
	v_add_f32_e32 v108, v222, v223
	s_add_u32 s100, s100, 0x8000
	s_addc_u32 s101, s101, 0
	s_waitcnt vmcnt(14)
	v_lshlrev_b32_e32 v142, 16, v164
	v_and_b32_e32 v143, 0xffff0000, v164
	v_pk_add_f32 v[92:93], v[92:93], v[142:143]
	v_pk_mul_f32 v[222:223], v[92:93], v[92:93]
	v_cvt_pk_bf16_f32 v164, v92, v93
	v_lshlrev_b32_e32 v142, 16, v165
	v_and_b32_e32 v143, 0xffff0000, v165
	v_pk_add_f32 v[94:95], v[94:95], v[142:143]
	v_pk_fma_f32 v[222:223], v[94:95], v[94:95], v[222:223]
	v_cvt_pk_bf16_f32 v165, v94, v95
	v_lshlrev_b32_e32 v142, 16, v166
	v_and_b32_e32 v143, 0xffff0000, v166
	v_pk_add_f32 v[88:89], v[88:89], v[142:143]
	v_pk_fma_f32 v[222:223], v[88:89], v[88:89], v[222:223]
	v_cvt_pk_bf16_f32 v166, v88, v89
	v_lshlrev_b32_e32 v142, 16, v167
	v_and_b32_e32 v143, 0xffff0000, v167
	v_pk_add_f32 v[90:91], v[90:91], v[142:143]
	v_pk_fma_f32 v[222:223], v[90:91], v[90:91], v[222:223]
	v_cvt_pk_bf16_f32 v167, v90, v91
	global_store_dwordx4 v138, v[164:167], s[100:101]
	v_lshlrev_b32_e32 v142, 16, v168
	v_and_b32_e32 v143, 0xffff0000, v168
	v_pk_add_f32 v[84:85], v[84:85], v[142:143]
	v_pk_fma_f32 v[222:223], v[84:85], v[84:85], v[222:223]
	v_cvt_pk_bf16_f32 v168, v84, v85
	v_lshlrev_b32_e32 v142, 16, v169
	v_and_b32_e32 v143, 0xffff0000, v169
	v_pk_add_f32 v[86:87], v[86:87], v[142:143]
	v_pk_fma_f32 v[222:223], v[86:87], v[86:87], v[222:223]
	v_cvt_pk_bf16_f32 v169, v86, v87
	v_lshlrev_b32_e32 v142, 16, v170
	v_and_b32_e32 v143, 0xffff0000, v170
	v_pk_add_f32 v[80:81], v[80:81], v[142:143]
	v_pk_fma_f32 v[222:223], v[80:81], v[80:81], v[222:223]
	v_cvt_pk_bf16_f32 v170, v80, v81
	v_lshlrev_b32_e32 v142, 16, v171
	v_and_b32_e32 v143, 0xffff0000, v171
	v_pk_add_f32 v[82:83], v[82:83], v[142:143]
	v_pk_fma_f32 v[222:223], v[82:83], v[82:83], v[222:223]
	v_cvt_pk_bf16_f32 v171, v82, v83
	global_store_dwordx4 v138, v[168:171], s[100:101] offset:256
	v_add_f32_e32 v92, v222, v223
	s_add_u32 s100, s100, 0x8000
	s_addc_u32 s101, s101, 0
	s_waitcnt vmcnt(14)
	v_lshlrev_b32_e32 v142, 16, v172
	v_and_b32_e32 v143, 0xffff0000, v172
	v_pk_add_f32 v[76:77], v[76:77], v[142:143]
	v_pk_mul_f32 v[222:223], v[76:77], v[76:77]
	v_cvt_pk_bf16_f32 v172, v76, v77
	v_lshlrev_b32_e32 v142, 16, v173
	v_and_b32_e32 v143, 0xffff0000, v173
	v_pk_add_f32 v[78:79], v[78:79], v[142:143]
	v_pk_fma_f32 v[222:223], v[78:79], v[78:79], v[222:223]
	v_cvt_pk_bf16_f32 v173, v78, v79
	v_lshlrev_b32_e32 v142, 16, v174
	v_and_b32_e32 v143, 0xffff0000, v174
	v_pk_add_f32 v[72:73], v[72:73], v[142:143]
	v_pk_fma_f32 v[222:223], v[72:73], v[72:73], v[222:223]
	v_cvt_pk_bf16_f32 v174, v72, v73
	v_lshlrev_b32_e32 v142, 16, v175
	v_and_b32_e32 v143, 0xffff0000, v175
	v_pk_add_f32 v[74:75], v[74:75], v[142:143]
	v_pk_fma_f32 v[222:223], v[74:75], v[74:75], v[222:223]
	v_cvt_pk_bf16_f32 v175, v74, v75
	global_store_dwordx4 v138, v[172:175], s[100:101]
	v_lshlrev_b32_e32 v142, 16, v176
	v_and_b32_e32 v143, 0xffff0000, v176
	v_pk_add_f32 v[68:69], v[68:69], v[142:143]
	v_pk_fma_f32 v[222:223], v[68:69], v[68:69], v[222:223]
	v_cvt_pk_bf16_f32 v176, v68, v69
	v_lshlrev_b32_e32 v142, 16, v177
	v_and_b32_e32 v143, 0xffff0000, v177
	v_pk_add_f32 v[70:71], v[70:71], v[142:143]
	v_pk_fma_f32 v[222:223], v[70:71], v[70:71], v[222:223]
	v_cvt_pk_bf16_f32 v177, v70, v71
	v_lshlrev_b32_e32 v142, 16, v178
	v_and_b32_e32 v143, 0xffff0000, v178
	v_pk_add_f32 v[64:65], v[64:65], v[142:143]
	v_pk_fma_f32 v[222:223], v[64:65], v[64:65], v[222:223]
	v_cvt_pk_bf16_f32 v178, v64, v65
	v_lshlrev_b32_e32 v142, 16, v179
	v_and_b32_e32 v143, 0xffff0000, v179
	v_pk_add_f32 v[66:67], v[66:67], v[142:143]
	v_pk_fma_f32 v[222:223], v[66:67], v[66:67], v[222:223]
	v_cvt_pk_bf16_f32 v179, v66, v67
	global_store_dwordx4 v138, v[176:179], s[100:101] offset:256
	v_add_f32_e32 v76, v222, v223
	s_add_u32 s100, s100, 0x28000
	s_addc_u32 s101, s101, 0
	s_waitcnt vmcnt(14)
	v_lshlrev_b32_e32 v142, 16, v180
	v_and_b32_e32 v143, 0xffff0000, v180
	v_pk_add_f32 v[60:61], v[60:61], v[142:143]
	v_pk_mul_f32 v[222:223], v[60:61], v[60:61]
	v_cvt_pk_bf16_f32 v180, v60, v61
	v_lshlrev_b32_e32 v142, 16, v181
	v_and_b32_e32 v143, 0xffff0000, v181
	v_pk_add_f32 v[62:63], v[62:63], v[142:143]
	v_pk_fma_f32 v[222:223], v[62:63], v[62:63], v[222:223]
	v_cvt_pk_bf16_f32 v181, v62, v63
	v_lshlrev_b32_e32 v142, 16, v182
	v_and_b32_e32 v143, 0xffff0000, v182
	v_pk_add_f32 v[56:57], v[56:57], v[142:143]
	v_pk_fma_f32 v[222:223], v[56:57], v[56:57], v[222:223]
	v_cvt_pk_bf16_f32 v182, v56, v57
	v_lshlrev_b32_e32 v142, 16, v183
	v_and_b32_e32 v143, 0xffff0000, v183
	v_pk_add_f32 v[58:59], v[58:59], v[142:143]
	v_pk_fma_f32 v[222:223], v[58:59], v[58:59], v[222:223]
	v_cvt_pk_bf16_f32 v183, v58, v59
	global_store_dwordx4 v138, v[180:183], s[100:101]
	v_lshlrev_b32_e32 v142, 16, v184
	v_and_b32_e32 v143, 0xffff0000, v184
	v_pk_add_f32 v[52:53], v[52:53], v[142:143]
	v_pk_fma_f32 v[222:223], v[52:53], v[52:53], v[222:223]
	v_cvt_pk_bf16_f32 v184, v52, v53
	v_lshlrev_b32_e32 v142, 16, v185
	v_and_b32_e32 v143, 0xffff0000, v185
	v_pk_add_f32 v[54:55], v[54:55], v[142:143]
	v_pk_fma_f32 v[222:223], v[54:55], v[54:55], v[222:223]
	v_cvt_pk_bf16_f32 v185, v54, v55
	v_lshlrev_b32_e32 v142, 16, v186
	v_and_b32_e32 v143, 0xffff0000, v186
	v_pk_add_f32 v[48:49], v[48:49], v[142:143]
	v_pk_fma_f32 v[222:223], v[48:49], v[48:49], v[222:223]
	v_cvt_pk_bf16_f32 v186, v48, v49
	v_lshlrev_b32_e32 v142, 16, v187
	v_and_b32_e32 v143, 0xffff0000, v187
	v_pk_add_f32 v[50:51], v[50:51], v[142:143]
	v_pk_fma_f32 v[222:223], v[50:51], v[50:51], v[222:223]
	v_cvt_pk_bf16_f32 v187, v50, v51
	global_store_dwordx4 v138, v[184:187], s[100:101] offset:256
	v_add_f32_e32 v60, v222, v223
	s_add_u32 s100, s100, 0x8000
	s_addc_u32 s101, s101, 0
	s_waitcnt vmcnt(14)
	v_lshlrev_b32_e32 v142, 16, v188
	v_and_b32_e32 v143, 0xffff0000, v188
	v_pk_add_f32 v[44:45], v[44:45], v[142:143]
	v_pk_mul_f32 v[222:223], v[44:45], v[44:45]
	v_cvt_pk_bf16_f32 v188, v44, v45
	v_lshlrev_b32_e32 v142, 16, v189
	v_and_b32_e32 v143, 0xffff0000, v189
	v_pk_add_f32 v[46:47], v[46:47], v[142:143]
	v_pk_fma_f32 v[222:223], v[46:47], v[46:47], v[222:223]
	v_cvt_pk_bf16_f32 v189, v46, v47
	v_lshlrev_b32_e32 v142, 16, v190
	v_and_b32_e32 v143, 0xffff0000, v190
	v_pk_add_f32 v[40:41], v[40:41], v[142:143]
	v_pk_fma_f32 v[222:223], v[40:41], v[40:41], v[222:223]
	v_cvt_pk_bf16_f32 v190, v40, v41
	v_lshlrev_b32_e32 v142, 16, v191
	v_and_b32_e32 v143, 0xffff0000, v191
	v_pk_add_f32 v[42:43], v[42:43], v[142:143]
	v_pk_fma_f32 v[222:223], v[42:43], v[42:43], v[222:223]
	v_cvt_pk_bf16_f32 v191, v42, v43
	global_store_dwordx4 v138, v[188:191], s[100:101]
	v_lshlrev_b32_e32 v142, 16, v192
	v_and_b32_e32 v143, 0xffff0000, v192
	v_pk_add_f32 v[36:37], v[36:37], v[142:143]
	v_pk_fma_f32 v[222:223], v[36:37], v[36:37], v[222:223]
	v_cvt_pk_bf16_f32 v192, v36, v37
	v_lshlrev_b32_e32 v142, 16, v193
	v_and_b32_e32 v143, 0xffff0000, v193
	v_pk_add_f32 v[38:39], v[38:39], v[142:143]
	v_pk_fma_f32 v[222:223], v[38:39], v[38:39], v[222:223]
	v_cvt_pk_bf16_f32 v193, v38, v39
	v_lshlrev_b32_e32 v142, 16, v194
	v_and_b32_e32 v143, 0xffff0000, v194
	v_pk_add_f32 v[32:33], v[32:33], v[142:143]
	v_pk_fma_f32 v[222:223], v[32:33], v[32:33], v[222:223]
	v_cvt_pk_bf16_f32 v194, v32, v33
	v_lshlrev_b32_e32 v142, 16, v195
	v_and_b32_e32 v143, 0xffff0000, v195
	v_pk_add_f32 v[34:35], v[34:35], v[142:143]
	v_pk_fma_f32 v[222:223], v[34:35], v[34:35], v[222:223]
	v_cvt_pk_bf16_f32 v195, v34, v35
	global_store_dwordx4 v138, v[192:195], s[100:101] offset:256
	v_add_f32_e32 v44, v222, v223
	s_add_u32 s100, s100, 0x8000
	s_addc_u32 s101, s101, 0
	s_waitcnt vmcnt(14)
	v_lshlrev_b32_e32 v142, 16, v196
	v_and_b32_e32 v143, 0xffff0000, v196
	v_pk_add_f32 v[28:29], v[28:29], v[142:143]
	v_pk_mul_f32 v[222:223], v[28:29], v[28:29]
	v_cvt_pk_bf16_f32 v196, v28, v29
	v_lshlrev_b32_e32 v142, 16, v197
	v_and_b32_e32 v143, 0xffff0000, v197
	v_pk_add_f32 v[30:31], v[30:31], v[142:143]
	v_pk_fma_f32 v[222:223], v[30:31], v[30:31], v[222:223]
	v_cvt_pk_bf16_f32 v197, v30, v31
	v_lshlrev_b32_e32 v142, 16, v198
	v_and_b32_e32 v143, 0xffff0000, v198
	v_pk_add_f32 v[24:25], v[24:25], v[142:143]
	v_pk_fma_f32 v[222:223], v[24:25], v[24:25], v[222:223]
	v_cvt_pk_bf16_f32 v198, v24, v25
	v_lshlrev_b32_e32 v142, 16, v199
	v_and_b32_e32 v143, 0xffff0000, v199
	v_pk_add_f32 v[26:27], v[26:27], v[142:143]
	v_pk_fma_f32 v[222:223], v[26:27], v[26:27], v[222:223]
	v_cvt_pk_bf16_f32 v199, v26, v27
	global_store_dwordx4 v138, v[196:199], s[100:101]
	v_lshlrev_b32_e32 v142, 16, v200
	v_and_b32_e32 v143, 0xffff0000, v200
	v_pk_add_f32 v[20:21], v[20:21], v[142:143]
	v_pk_fma_f32 v[222:223], v[20:21], v[20:21], v[222:223]
	v_cvt_pk_bf16_f32 v200, v20, v21
	v_lshlrev_b32_e32 v142, 16, v201
	v_and_b32_e32 v143, 0xffff0000, v201
	v_pk_add_f32 v[22:23], v[22:23], v[142:143]
	v_pk_fma_f32 v[222:223], v[22:23], v[22:23], v[222:223]
	v_cvt_pk_bf16_f32 v201, v22, v23
	v_lshlrev_b32_e32 v142, 16, v202
	v_and_b32_e32 v143, 0xffff0000, v202
	v_pk_add_f32 v[16:17], v[16:17], v[142:143]
	v_pk_fma_f32 v[222:223], v[16:17], v[16:17], v[222:223]
	v_cvt_pk_bf16_f32 v202, v16, v17
	v_lshlrev_b32_e32 v142, 16, v203
	v_and_b32_e32 v143, 0xffff0000, v203
	v_pk_add_f32 v[18:19], v[18:19], v[142:143]
	v_pk_fma_f32 v[222:223], v[18:19], v[18:19], v[222:223]
	v_cvt_pk_bf16_f32 v203, v18, v19
	global_store_dwordx4 v138, v[200:203], s[100:101] offset:256
	v_add_f32_e32 v28, v222, v223
	s_add_u32 s100, s100, 0x8000
	s_addc_u32 s101, s101, 0
	s_waitcnt vmcnt(14)
	v_lshlrev_b32_e32 v142, 16, v204
	v_and_b32_e32 v143, 0xffff0000, v204
	v_pk_add_f32 v[12:13], v[12:13], v[142:143]
	v_pk_mul_f32 v[222:223], v[12:13], v[12:13]
	v_cvt_pk_bf16_f32 v204, v12, v13
	v_lshlrev_b32_e32 v142, 16, v205
	v_and_b32_e32 v143, 0xffff0000, v205
	v_pk_add_f32 v[14:15], v[14:15], v[142:143]
	v_pk_fma_f32 v[222:223], v[14:15], v[14:15], v[222:223]
	v_cvt_pk_bf16_f32 v205, v14, v15
	v_lshlrev_b32_e32 v142, 16, v206
	v_and_b32_e32 v143, 0xffff0000, v206
	v_pk_add_f32 v[8:9], v[8:9], v[142:143]
	v_pk_fma_f32 v[222:223], v[8:9], v[8:9], v[222:223]
	v_cvt_pk_bf16_f32 v206, v8, v9
	v_lshlrev_b32_e32 v142, 16, v207
	v_and_b32_e32 v143, 0xffff0000, v207
	v_pk_add_f32 v[10:11], v[10:11], v[142:143]
	v_pk_fma_f32 v[222:223], v[10:11], v[10:11], v[222:223]
	v_cvt_pk_bf16_f32 v207, v10, v11
	global_store_dwordx4 v138, v[204:207], s[100:101]
	v_lshlrev_b32_e32 v142, 16, v236
	v_and_b32_e32 v143, 0xffff0000, v236
	v_pk_add_f32 v[4:5], v[4:5], v[142:143]
	v_pk_fma_f32 v[222:223], v[4:5], v[4:5], v[222:223]
	v_cvt_pk_bf16_f32 v236, v4, v5
	v_lshlrev_b32_e32 v142, 16, v237
	v_and_b32_e32 v143, 0xffff0000, v237
	v_pk_add_f32 v[6:7], v[6:7], v[142:143]
	v_pk_fma_f32 v[222:223], v[6:7], v[6:7], v[222:223]
	v_cvt_pk_bf16_f32 v237, v6, v7
	v_lshlrev_b32_e32 v142, 16, v238
	v_and_b32_e32 v143, 0xffff0000, v238
	v_pk_add_f32 v[0:1], v[0:1], v[142:143]
	v_pk_fma_f32 v[222:223], v[0:1], v[0:1], v[222:223]
	v_cvt_pk_bf16_f32 v238, v0, v1
	v_lshlrev_b32_e32 v142, 16, v239
	v_and_b32_e32 v143, 0xffff0000, v239
	v_pk_add_f32 v[2:3], v[2:3], v[142:143]
	v_pk_fma_f32 v[222:223], v[2:3], v[2:3], v[222:223]
	v_cvt_pk_bf16_f32 v239, v2, v3
	global_store_dwordx4 v138, v[236:239], s[100:101] offset:256
	v_add_f32_e32 v12, v222, v223
	v_mov_b32_e32 v125, v124
	v_mov_b32_e32 v109, v108
	v_mov_b32_e32 v93, v92
	v_mov_b32_e32 v77, v76
	v_mov_b32_e32 v61, v60
	v_mov_b32_e32 v45, v44
	v_mov_b32_e32 v29, v28
	v_mov_b32_e32 v13, v12
	s_nop 1
	v_permlane16_swap_b32 v125, v124
	v_permlane16_swap_b32 v109, v108
	v_permlane16_swap_b32 v93, v92
	v_permlane16_swap_b32 v77, v76
	v_permlane16_swap_b32 v61, v60
	v_permlane16_swap_b32 v45, v44
	v_permlane16_swap_b32 v29, v28
	v_permlane16_swap_b32 v13, v12
	s_waitcnt lgkmcnt(0)
	v_add_f32_e32 v124, v124, v125
	v_add_f32_e32 v108, v108, v109
	v_add_f32_e32 v92, v92, v93
	v_add_f32_e32 v76, v76, v77
	v_add_f32_e32 v60, v60, v61
	v_add_f32_e32 v44, v44, v45
	v_add_f32_e32 v28, v28, v29
	v_add_f32_e32 v12, v12, v13
	v_mov_b32_e32 v125, v124
	v_mov_b32_e32 v109, v108
	v_mov_b32_e32 v93, v92
	v_mov_b32_e32 v77, v76
	v_mov_b32_e32 v61, v60
	v_mov_b32_e32 v45, v44
	v_mov_b32_e32 v29, v28
	v_mov_b32_e32 v13, v12
	s_nop 1
	v_permlane32_swap_b32 v125, v124
	v_permlane32_swap_b32 v109, v108
	v_permlane32_swap_b32 v93, v92
	v_permlane32_swap_b32 v77, v76
	v_permlane32_swap_b32 v61, v60
	v_permlane32_swap_b32 v45, v44
	v_permlane32_swap_b32 v29, v28
	v_permlane32_swap_b32 v13, v12
	s_waitcnt lgkmcnt(0)
	v_add_f32_e32 v124, v124, v125
	v_add_f32_e32 v108, v108, v109
	v_add_f32_e32 v92, v92, v93
	v_add_f32_e32 v76, v76, v77
	v_add_f32_e32 v60, v60, v61
	v_add_f32_e32 v44, v44, v45
	v_add_f32_e32 v28, v28, v29
	v_add_f32_e32 v12, v12, v13
	s_and_saveexec_b64 s[98:99], s[4:5]
	global_atomic_add_f32 v139, v124, s[76:77]
	global_atomic_add_f32 v139, v108, s[76:77] offset:64
	global_atomic_add_f32 v139, v92, s[76:77] offset:128
	global_atomic_add_f32 v139, v76, s[76:77] offset:192
	global_atomic_add_f32 v139, v60, s[76:77] offset:512
	global_atomic_add_f32 v139, v44, s[76:77] offset:576
	global_atomic_add_f32 v139, v28, s[76:77] offset:640
	global_atomic_add_f32 v139, v12, s[76:77] offset:704
	s_or_b64 exec, exec, s[98:99]
	s_andn2_b64 vcc, exec, s[6:7]
	s_mov_b64 s[6:7], -1
	s_cbranch_vccnz .LBB0_702
	s_andn2_b64 vcc, exec, s[0:1]
	s_cbranch_vccnz .LBB0_701
	s_barrier
	s_branch .LBB0_701

.LBB0_872:
	v_xor_b32_e32 v140, 16, v230
	v_xor_b32_e32 v141, 32, v230
	v_lshlrev_b32_e32 v140, 2, v140
	v_lshlrev_b32_e32 v141, 2, v141
	s_mov_b64 s[100:101], s[46:47]
	s_waitcnt vmcnt(14)
	v_lshlrev_b32_e32 v142, 16, v148
	v_and_b32_e32 v143, 0xffff0000, v148
	v_pk_add_f32 v[124:125], v[124:125], v[142:143]
	v_pk_mul_f32 v[222:223], v[124:125], v[124:125]
	v_cvt_pk_bf16_f32 v148, v124, v125
	v_lshlrev_b32_e32 v142, 16, v149
	v_and_b32_e32 v143, 0xffff0000, v149
	v_pk_add_f32 v[126:127], v[126:127], v[142:143]
	v_pk_fma_f32 v[222:223], v[126:127], v[126:127], v[222:223]
	v_cvt_pk_bf16_f32 v149, v126, v127
	v_lshlrev_b32_e32 v142, 16, v150
	v_and_b32_e32 v143, 0xffff0000, v150
	v_pk_add_f32 v[120:121], v[120:121], v[142:143]
	v_pk_fma_f32 v[222:223], v[120:121], v[120:121], v[222:223]
	v_cvt_pk_bf16_f32 v150, v120, v121
	v_lshlrev_b32_e32 v142, 16, v151
	v_and_b32_e32 v143, 0xffff0000, v151
	v_pk_add_f32 v[122:123], v[122:123], v[142:143]
	v_pk_fma_f32 v[222:223], v[122:123], v[122:123], v[222:223]
	v_cvt_pk_bf16_f32 v151, v122, v123
	global_store_dwordx4 v138, v[148:151], s[100:101]
	v_lshlrev_b32_e32 v142, 16, v152
	v_and_b32_e32 v143, 0xffff0000, v152
	v_pk_add_f32 v[116:117], v[116:117], v[142:143]
	v_pk_fma_f32 v[222:223], v[116:117], v[116:117], v[222:223]
	v_cvt_pk_bf16_f32 v152, v116, v117
	v_lshlrev_b32_e32 v142, 16, v153
	v_and_b32_e32 v143, 0xffff0000, v153
	v_pk_add_f32 v[118:119], v[118:119], v[142:143]
	v_pk_fma_f32 v[222:223], v[118:119], v[118:119], v[222:223]
	v_cvt_pk_bf16_f32 v153, v118, v119
	v_lshlrev_b32_e32 v142, 16, v154
	v_and_b32_e32 v143, 0xffff0000, v154
	v_pk_add_f32 v[112:113], v[112:113], v[142:143]
	v_pk_fma_f32 v[222:223], v[112:113], v[112:113], v[222:223]
	v_cvt_pk_bf16_f32 v154, v112, v113
	v_lshlrev_b32_e32 v142, 16, v155
	v_and_b32_e32 v143, 0xffff0000, v155
	v_pk_add_f32 v[114:115], v[114:115], v[142:143]
	v_pk_fma_f32 v[222:223], v[114:115], v[114:115], v[222:223]
	v_cvt_pk_bf16_f32 v155, v114, v115
	global_store_dwordx4 v138, v[152:155], s[100:101] offset:256
	v_add_f32_e32 v124, v222, v223
	s_add_u32 s100, s100, 0x8000
	s_addc_u32 s101, s101, 0
	s_waitcnt vmcnt(14)
	v_lshlrev_b32_e32 v142, 16, v156
	v_and_b32_e32 v143, 0xffff0000, v156
	v_pk_add_f32 v[108:109], v[108:109], v[142:143]
	v_pk_mul_f32 v[222:223], v[108:109], v[108:109]
	v_cvt_pk_bf16_f32 v156, v108, v109
	v_lshlrev_b32_e32 v142, 16, v157
	v_and_b32_e32 v143, 0xffff0000, v157
	v_pk_add_f32 v[110:111], v[110:111], v[142:143]
	v_pk_fma_f32 v[222:223], v[110:111], v[110:111], v[222:223]
	v_cvt_pk_bf16_f32 v157, v110, v111
	v_lshlrev_b32_e32 v142, 16, v158
	v_and_b32_e32 v143, 0xffff0000, v158
	v_pk_add_f32 v[104:105], v[104:105], v[142:143]
	v_pk_fma_f32 v[222:223], v[104:105], v[104:105], v[222:223]
	v_cvt_pk_bf16_f32 v158, v104, v105
	v_lshlrev_b32_e32 v142, 16, v159
	v_and_b32_e32 v143, 0xffff0000, v159
	v_pk_add_f32 v[106:107], v[106:107], v[142:143]
	v_pk_fma_f32 v[222:223], v[106:107], v[106:107], v[222:223]
	v_cvt_pk_bf16_f32 v159, v106, v107
	global_store_dwordx4 v138, v[156:159], s[100:101]
	v_lshlrev_b32_e32 v142, 16, v160
	v_and_b32_e32 v143, 0xffff0000, v160
	v_pk_add_f32 v[100:101], v[100:101], v[142:143]
	v_pk_fma_f32 v[222:223], v[100:101], v[100:101], v[222:223]
	v_cvt_pk_bf16_f32 v160, v100, v101
	v_lshlrev_b32_e32 v142, 16, v161
	v_and_b32_e32 v143, 0xffff0000, v161
	v_pk_add_f32 v[102:103], v[102:103], v[142:143]
	v_pk_fma_f32 v[222:223], v[102:103], v[102:103], v[222:223]
	v_cvt_pk_bf16_f32 v161, v102, v103
	v_lshlrev_b32_e32 v142, 16, v162
	v_and_b32_e32 v143, 0xffff0000, v162
	v_pk_add_f32 v[96:97], v[96:97], v[142:143]
	v_pk_fma_f32 v[222:223], v[96:97], v[96:97], v[222:223]
	v_cvt_pk_bf16_f32 v162, v96, v97
	v_lshlrev_b32_e32 v142, 16, v163
	v_and_b32_e32 v143, 0xffff0000, v163
	v_pk_add_f32 v[98:99], v[98:99], v[142:143]
	v_pk_fma_f32 v[222:223], v[98:99], v[98:99], v[222:223]
	v_cvt_pk_bf16_f32 v163, v98, v99
	global_store_dwordx4 v138, v[160:163], s[100:101] offset:256
	v_add_f32_e32 v108, v222, v223
	s_add_u32 s100, s100, 0x8000
	s_addc_u32 s101, s101, 0
	s_waitcnt vmcnt(14)
	v_lshlrev_b32_e32 v142, 16, v164
	v_and_b32_e32 v143, 0xffff0000, v164
	v_pk_add_f32 v[92:93], v[92:93], v[142:143]
	v_pk_mul_f32 v[222:223], v[92:93], v[92:93]
	v_cvt_pk_bf16_f32 v164, v92, v93
	v_lshlrev_b32_e32 v142, 16, v165
	v_and_b32_e32 v143, 0xffff0000, v165
	v_pk_add_f32 v[94:95], v[94:95], v[142:143]
	v_pk_fma_f32 v[222:223], v[94:95], v[94:95], v[222:223]
	v_cvt_pk_bf16_f32 v165, v94, v95
	v_lshlrev_b32_e32 v142, 16, v166
	v_and_b32_e32 v143, 0xffff0000, v166
	v_pk_add_f32 v[88:89], v[88:89], v[142:143]
	v_pk_fma_f32 v[222:223], v[88:89], v[88:89], v[222:223]
	v_cvt_pk_bf16_f32 v166, v88, v89
	v_lshlrev_b32_e32 v142, 16, v167
	v_and_b32_e32 v143, 0xffff0000, v167
	v_pk_add_f32 v[90:91], v[90:91], v[142:143]
	v_pk_fma_f32 v[222:223], v[90:91], v[90:91], v[222:223]
	v_cvt_pk_bf16_f32 v167, v90, v91
	global_store_dwordx4 v138, v[164:167], s[100:101]
	v_lshlrev_b32_e32 v142, 16, v168
	v_and_b32_e32 v143, 0xffff0000, v168
	v_pk_add_f32 v[84:85], v[84:85], v[142:143]
	v_pk_fma_f32 v[222:223], v[84:85], v[84:85], v[222:223]
	v_cvt_pk_bf16_f32 v168, v84, v85
	v_lshlrev_b32_e32 v142, 16, v169
	v_and_b32_e32 v143, 0xffff0000, v169
	v_pk_add_f32 v[86:87], v[86:87], v[142:143]
	v_pk_fma_f32 v[222:223], v[86:87], v[86:87], v[222:223]
	v_cvt_pk_bf16_f32 v169, v86, v87
	v_lshlrev_b32_e32 v142, 16, v170
	v_and_b32_e32 v143, 0xffff0000, v170
	v_pk_add_f32 v[80:81], v[80:81], v[142:143]
	v_pk_fma_f32 v[222:223], v[80:81], v[80:81], v[222:223]
	v_cvt_pk_bf16_f32 v170, v80, v81
	v_lshlrev_b32_e32 v142, 16, v171
	v_and_b32_e32 v143, 0xffff0000, v171
	v_pk_add_f32 v[82:83], v[82:83], v[142:143]
	v_pk_fma_f32 v[222:223], v[82:83], v[82:83], v[222:223]
	v_cvt_pk_bf16_f32 v171, v82, v83
	global_store_dwordx4 v138, v[168:171], s[100:101] offset:256
	v_add_f32_e32 v92, v222, v223
	s_add_u32 s100, s100, 0x8000
	s_addc_u32 s101, s101, 0
	s_waitcnt vmcnt(14)
	v_lshlrev_b32_e32 v142, 16, v172
	v_and_b32_e32 v143, 0xffff0000, v172
	v_pk_add_f32 v[76:77], v[76:77], v[142:143]
	v_pk_mul_f32 v[222:223], v[76:77], v[76:77]
	v_cvt_pk_bf16_f32 v172, v76, v77
	v_lshlrev_b32_e32 v142, 16, v173
	v_and_b32_e32 v143, 0xffff0000, v173
	v_pk_add_f32 v[78:79], v[78:79], v[142:143]
	v_pk_fma_f32 v[222:223], v[78:79], v[78:79], v[222:223]
	v_cvt_pk_bf16_f32 v173, v78, v79
	v_lshlrev_b32_e32 v142, 16, v174
	v_and_b32_e32 v143, 0xffff0000, v174
	v_pk_add_f32 v[72:73], v[72:73], v[142:143]
	v_pk_fma_f32 v[222:223], v[72:73], v[72:73], v[222:223]
	v_cvt_pk_bf16_f32 v174, v72, v73
	v_lshlrev_b32_e32 v142, 16, v175
	v_and_b32_e32 v143, 0xffff0000, v175
	v_pk_add_f32 v[74:75], v[74:75], v[142:143]
	v_pk_fma_f32 v[222:223], v[74:75], v[74:75], v[222:223]
	v_cvt_pk_bf16_f32 v175, v74, v75
	global_store_dwordx4 v138, v[172:175], s[100:101]
	v_lshlrev_b32_e32 v142, 16, v176
	v_and_b32_e32 v143, 0xffff0000, v176
	v_pk_add_f32 v[68:69], v[68:69], v[142:143]
	v_pk_fma_f32 v[222:223], v[68:69], v[68:69], v[222:223]
	v_cvt_pk_bf16_f32 v176, v68, v69
	v_lshlrev_b32_e32 v142, 16, v177
	v_and_b32_e32 v143, 0xffff0000, v177
	v_pk_add_f32 v[70:71], v[70:71], v[142:143]
	v_pk_fma_f32 v[222:223], v[70:71], v[70:71], v[222:223]
	v_cvt_pk_bf16_f32 v177, v70, v71
	v_lshlrev_b32_e32 v142, 16, v178
	v_and_b32_e32 v143, 0xffff0000, v178
	v_pk_add_f32 v[64:65], v[64:65], v[142:143]
	v_pk_fma_f32 v[222:223], v[64:65], v[64:65], v[222:223]
	v_cvt_pk_bf16_f32 v178, v64, v65
	v_lshlrev_b32_e32 v142, 16, v179
	v_and_b32_e32 v143, 0xffff0000, v179
	v_pk_add_f32 v[66:67], v[66:67], v[142:143]
	v_pk_fma_f32 v[222:223], v[66:67], v[66:67], v[222:223]
	v_cvt_pk_bf16_f32 v179, v66, v67
	global_store_dwordx4 v138, v[176:179], s[100:101] offset:256
	v_add_f32_e32 v76, v222, v223
	s_add_u32 s100, s100, 0x28000
	s_addc_u32 s101, s101, 0
	s_waitcnt vmcnt(14)
	v_lshlrev_b32_e32 v142, 16, v180
	v_and_b32_e32 v143, 0xffff0000, v180
	v_pk_add_f32 v[60:61], v[60:61], v[142:143]
	v_pk_mul_f32 v[222:223], v[60:61], v[60:61]
	v_cvt_pk_bf16_f32 v180, v60, v61
	v_lshlrev_b32_e32 v142, 16, v181
	v_and_b32_e32 v143, 0xffff0000, v181
	v_pk_add_f32 v[62:63], v[62:63], v[142:143]
	v_pk_fma_f32 v[222:223], v[62:63], v[62:63], v[222:223]
	v_cvt_pk_bf16_f32 v181, v62, v63
	v_lshlrev_b32_e32 v142, 16, v182
	v_and_b32_e32 v143, 0xffff0000, v182
	v_pk_add_f32 v[56:57], v[56:57], v[142:143]
	v_pk_fma_f32 v[222:223], v[56:57], v[56:57], v[222:223]
	v_cvt_pk_bf16_f32 v182, v56, v57
	v_lshlrev_b32_e32 v142, 16, v183
	v_and_b32_e32 v143, 0xffff0000, v183
	v_pk_add_f32 v[58:59], v[58:59], v[142:143]
	v_pk_fma_f32 v[222:223], v[58:59], v[58:59], v[222:223]
	v_cvt_pk_bf16_f32 v183, v58, v59
	global_store_dwordx4 v138, v[180:183], s[100:101]
	v_lshlrev_b32_e32 v142, 16, v184
	v_and_b32_e32 v143, 0xffff0000, v184
	v_pk_add_f32 v[52:53], v[52:53], v[142:143]
	v_pk_fma_f32 v[222:223], v[52:53], v[52:53], v[222:223]
	v_cvt_pk_bf16_f32 v184, v52, v53
	v_lshlrev_b32_e32 v142, 16, v185
	v_and_b32_e32 v143, 0xffff0000, v185
	v_pk_add_f32 v[54:55], v[54:55], v[142:143]
	v_pk_fma_f32 v[222:223], v[54:55], v[54:55], v[222:223]
	v_cvt_pk_bf16_f32 v185, v54, v55
	v_lshlrev_b32_e32 v142, 16, v186
	v_and_b32_e32 v143, 0xffff0000, v186
	v_pk_add_f32 v[48:49], v[48:49], v[142:143]
	v_pk_fma_f32 v[222:223], v[48:49], v[48:49], v[222:223]
	v_cvt_pk_bf16_f32 v186, v48, v49
	v_lshlrev_b32_e32 v142, 16, v187
	v_and_b32_e32 v143, 0xffff0000, v187
	v_pk_add_f32 v[50:51], v[50:51], v[142:143]
	v_pk_fma_f32 v[222:223], v[50:51], v[50:51], v[222:223]
	v_cvt_pk_bf16_f32 v187, v50, v51
	global_store_dwordx4 v138, v[184:187], s[100:101] offset:256
	v_add_f32_e32 v60, v222, v223
	s_add_u32 s100, s100, 0x8000
	s_addc_u32 s101, s101, 0
	s_waitcnt vmcnt(14)
	v_lshlrev_b32_e32 v142, 16, v188
	v_and_b32_e32 v143, 0xffff0000, v188
	v_pk_add_f32 v[44:45], v[44:45], v[142:143]
	v_pk_mul_f32 v[222:223], v[44:45], v[44:45]
	v_cvt_pk_bf16_f32 v188, v44, v45
	v_lshlrev_b32_e32 v142, 16, v189
	v_and_b32_e32 v143, 0xffff0000, v189
	v_pk_add_f32 v[46:47], v[46:47], v[142:143]
	v_pk_fma_f32 v[222:223], v[46:47], v[46:47], v[222:223]
	v_cvt_pk_bf16_f32 v189, v46, v47
	v_lshlrev_b32_e32 v142, 16, v190
	v_and_b32_e32 v143, 0xffff0000, v190
	v_pk_add_f32 v[40:41], v[40:41], v[142:143]
	v_pk_fma_f32 v[222:223], v[40:41], v[40:41], v[222:223]
	v_cvt_pk_bf16_f32 v190, v40, v41
	v_lshlrev_b32_e32 v142, 16, v191
	v_and_b32_e32 v143, 0xffff0000, v191
	v_pk_add_f32 v[42:43], v[42:43], v[142:143]
	v_pk_fma_f32 v[222:223], v[42:43], v[42:43], v[222:223]
	v_cvt_pk_bf16_f32 v191, v42, v43
	global_store_dwordx4 v138, v[188:191], s[100:101]
	v_lshlrev_b32_e32 v142, 16, v192
	v_and_b32_e32 v143, 0xffff0000, v192
	v_pk_add_f32 v[36:37], v[36:37], v[142:143]
	v_pk_fma_f32 v[222:223], v[36:37], v[36:37], v[222:223]
	v_cvt_pk_bf16_f32 v192, v36, v37
	v_lshlrev_b32_e32 v142, 16, v193
	v_and_b32_e32 v143, 0xffff0000, v193
	v_pk_add_f32 v[38:39], v[38:39], v[142:143]
	v_pk_fma_f32 v[222:223], v[38:39], v[38:39], v[222:223]
	v_cvt_pk_bf16_f32 v193, v38, v39
	v_lshlrev_b32_e32 v142, 16, v194
	v_and_b32_e32 v143, 0xffff0000, v194
	v_pk_add_f32 v[32:33], v[32:33], v[142:143]
	v_pk_fma_f32 v[222:223], v[32:33], v[32:33], v[222:223]
	v_cvt_pk_bf16_f32 v194, v32, v33
	v_lshlrev_b32_e32 v142, 16, v195
	v_and_b32_e32 v143, 0xffff0000, v195
	v_pk_add_f32 v[34:35], v[34:35], v[142:143]
	v_pk_fma_f32 v[222:223], v[34:35], v[34:35], v[222:223]
	v_cvt_pk_bf16_f32 v195, v34, v35
	global_store_dwordx4 v138, v[192:195], s[100:101] offset:256
	v_add_f32_e32 v44, v222, v223
	s_add_u32 s100, s100, 0x8000
	s_addc_u32 s101, s101, 0
	s_waitcnt vmcnt(14)
	v_lshlrev_b32_e32 v142, 16, v196
	v_and_b32_e32 v143, 0xffff0000, v196
	v_pk_add_f32 v[28:29], v[28:29], v[142:143]
	v_pk_mul_f32 v[222:223], v[28:29], v[28:29]
	v_cvt_pk_bf16_f32 v196, v28, v29
	v_lshlrev_b32_e32 v142, 16, v197
	v_and_b32_e32 v143, 0xffff0000, v197
	v_pk_add_f32 v[30:31], v[30:31], v[142:143]
	v_pk_fma_f32 v[222:223], v[30:31], v[30:31], v[222:223]
	v_cvt_pk_bf16_f32 v197, v30, v31
	v_lshlrev_b32_e32 v142, 16, v198
	v_and_b32_e32 v143, 0xffff0000, v198
	v_pk_add_f32 v[24:25], v[24:25], v[142:143]
	v_pk_fma_f32 v[222:223], v[24:25], v[24:25], v[222:223]
	v_cvt_pk_bf16_f32 v198, v24, v25
	v_lshlrev_b32_e32 v142, 16, v199
	v_and_b32_e32 v143, 0xffff0000, v199
	v_pk_add_f32 v[26:27], v[26:27], v[142:143]
	v_pk_fma_f32 v[222:223], v[26:27], v[26:27], v[222:223]
	v_cvt_pk_bf16_f32 v199, v26, v27
	global_store_dwordx4 v138, v[196:199], s[100:101]
	v_lshlrev_b32_e32 v142, 16, v200
	v_and_b32_e32 v143, 0xffff0000, v200
	v_pk_add_f32 v[20:21], v[20:21], v[142:143]
	v_pk_fma_f32 v[222:223], v[20:21], v[20:21], v[222:223]
	v_cvt_pk_bf16_f32 v200, v20, v21
	v_lshlrev_b32_e32 v142, 16, v201
	v_and_b32_e32 v143, 0xffff0000, v201
	v_pk_add_f32 v[22:23], v[22:23], v[142:143]
	v_pk_fma_f32 v[222:223], v[22:23], v[22:23], v[222:223]
	v_cvt_pk_bf16_f32 v201, v22, v23
	v_lshlrev_b32_e32 v142, 16, v202
	v_and_b32_e32 v143, 0xffff0000, v202
	v_pk_add_f32 v[16:17], v[16:17], v[142:143]
	v_pk_fma_f32 v[222:223], v[16:17], v[16:17], v[222:223]
	v_cvt_pk_bf16_f32 v202, v16, v17
	v_lshlrev_b32_e32 v142, 16, v203
	v_and_b32_e32 v143, 0xffff0000, v203
	v_pk_add_f32 v[18:19], v[18:19], v[142:143]
	v_pk_fma_f32 v[222:223], v[18:19], v[18:19], v[222:223]
	v_cvt_pk_bf16_f32 v203, v18, v19
	global_store_dwordx4 v138, v[200:203], s[100:101] offset:256
	v_add_f32_e32 v28, v222, v223
	s_add_u32 s100, s100, 0x8000
	s_addc_u32 s101, s101, 0
	s_waitcnt vmcnt(14)
	v_lshlrev_b32_e32 v142, 16, v204
	v_and_b32_e32 v143, 0xffff0000, v204
	v_pk_add_f32 v[12:13], v[12:13], v[142:143]
	v_pk_mul_f32 v[222:223], v[12:13], v[12:13]
	v_cvt_pk_bf16_f32 v204, v12, v13
	v_lshlrev_b32_e32 v142, 16, v205
	v_and_b32_e32 v143, 0xffff0000, v205
	v_pk_add_f32 v[14:15], v[14:15], v[142:143]
	v_pk_fma_f32 v[222:223], v[14:15], v[14:15], v[222:223]
	v_cvt_pk_bf16_f32 v205, v14, v15
	v_lshlrev_b32_e32 v142, 16, v206
	v_and_b32_e32 v143, 0xffff0000, v206
	v_pk_add_f32 v[8:9], v[8:9], v[142:143]
	v_pk_fma_f32 v[222:223], v[8:9], v[8:9], v[222:223]
	v_cvt_pk_bf16_f32 v206, v8, v9
	v_lshlrev_b32_e32 v142, 16, v207
	v_and_b32_e32 v143, 0xffff0000, v207
	v_pk_add_f32 v[10:11], v[10:11], v[142:143]
	v_pk_fma_f32 v[222:223], v[10:11], v[10:11], v[222:223]
	v_cvt_pk_bf16_f32 v207, v10, v11
	global_store_dwordx4 v138, v[204:207], s[100:101]
	v_lshlrev_b32_e32 v142, 16, v236
	v_and_b32_e32 v143, 0xffff0000, v236
	v_pk_add_f32 v[4:5], v[4:5], v[142:143]
	v_pk_fma_f32 v[222:223], v[4:5], v[4:5], v[222:223]
	v_cvt_pk_bf16_f32 v236, v4, v5
	v_lshlrev_b32_e32 v142, 16, v237
	v_and_b32_e32 v143, 0xffff0000, v237
	v_pk_add_f32 v[6:7], v[6:7], v[142:143]
	v_pk_fma_f32 v[222:223], v[6:7], v[6:7], v[222:223]
	v_cvt_pk_bf16_f32 v237, v6, v7
	v_lshlrev_b32_e32 v142, 16, v238
	v_and_b32_e32 v143, 0xffff0000, v238
	v_pk_add_f32 v[0:1], v[0:1], v[142:143]
	v_pk_fma_f32 v[222:223], v[0:1], v[0:1], v[222:223]
	v_cvt_pk_bf16_f32 v238, v0, v1
	v_lshlrev_b32_e32 v142, 16, v239
	v_and_b32_e32 v143, 0xffff0000, v239
	v_pk_add_f32 v[2:3], v[2:3], v[142:143]
	v_pk_fma_f32 v[222:223], v[2:3], v[2:3], v[222:223]
	v_cvt_pk_bf16_f32 v239, v2, v3
	global_store_dwordx4 v138, v[236:239], s[100:101] offset:256
	v_add_f32_e32 v12, v222, v223
	v_mov_b32_e32 v125, v124
	v_mov_b32_e32 v109, v108
	v_mov_b32_e32 v93, v92
	v_mov_b32_e32 v77, v76
	v_mov_b32_e32 v61, v60
	v_mov_b32_e32 v45, v44
	v_mov_b32_e32 v29, v28
	v_mov_b32_e32 v13, v12
	s_nop 1
	v_permlane16_swap_b32 v125, v124
	v_permlane16_swap_b32 v109, v108
	v_permlane16_swap_b32 v93, v92
	v_permlane16_swap_b32 v77, v76
	v_permlane16_swap_b32 v61, v60
	v_permlane16_swap_b32 v45, v44
	v_permlane16_swap_b32 v29, v28
	v_permlane16_swap_b32 v13, v12
	s_waitcnt lgkmcnt(0)
	v_add_f32_e32 v124, v124, v125
	v_add_f32_e32 v108, v108, v109
	v_add_f32_e32 v92, v92, v93
	v_add_f32_e32 v76, v76, v77
	v_add_f32_e32 v60, v60, v61
	v_add_f32_e32 v44, v44, v45
	v_add_f32_e32 v28, v28, v29
	v_add_f32_e32 v12, v12, v13
	v_mov_b32_e32 v125, v124
	v_mov_b32_e32 v109, v108
	v_mov_b32_e32 v93, v92
	v_mov_b32_e32 v77, v76
	v_mov_b32_e32 v61, v60
	v_mov_b32_e32 v45, v44
	v_mov_b32_e32 v29, v28
	v_mov_b32_e32 v13, v12
	s_nop 1
	v_permlane32_swap_b32 v125, v124
	v_permlane32_swap_b32 v109, v108
	v_permlane32_swap_b32 v93, v92
	v_permlane32_swap_b32 v77, v76
	v_permlane32_swap_b32 v61, v60
	v_permlane32_swap_b32 v45, v44
	v_permlane32_swap_b32 v29, v28
	v_permlane32_swap_b32 v13, v12
	s_waitcnt lgkmcnt(0)
	v_add_f32_e32 v124, v124, v125
	v_add_f32_e32 v108, v108, v109
	v_add_f32_e32 v92, v92, v93
	v_add_f32_e32 v76, v76, v77
	v_add_f32_e32 v60, v60, v61
	v_add_f32_e32 v44, v44, v45
	v_add_f32_e32 v28, v28, v29
	v_add_f32_e32 v12, v12, v13
	s_and_saveexec_b64 s[98:99], s[4:5]
	global_atomic_add_f32 v139, v124, s[12:13]
	global_atomic_add_f32 v139, v108, s[12:13] offset:64
	global_atomic_add_f32 v139, v92, s[12:13] offset:128
	global_atomic_add_f32 v139, v76, s[12:13] offset:192
	global_atomic_add_f32 v139, v60, s[12:13] offset:512
	global_atomic_add_f32 v139, v44, s[12:13] offset:576
	global_atomic_add_f32 v139, v28, s[12:13] offset:640
	global_atomic_add_f32 v139, v12, s[12:13] offset:704
	s_or_b64 exec, exec, s[98:99]
	v_readlane_b32 s76, v252, 46
	s_mov_b32 s77, 0x20000
	s_mov_b32 s28, 0x30000
	s_mov_b32 s29, 0x40000
	s_mov_b32 s72, 0x50000
	s_andn2_b64 vcc, exec, s[6:7]
	s_mov_b64 s[6:7], -1
	s_cbranch_vccnz .LBB0_861
	s_andn2_b64 vcc, exec, s[0:1]
	s_cbranch_vccnz .LBB0_860
	s_barrier
	s_branch .LBB0_860
